# code placement, opposite phase: every K-loop MFMA run starts at 4 mod 8
# speedup vs baseline: 1.0013x; 1.0013x over previous
; #define PG8_STAGE(bufoff, gbase, voff) do { _Pragma("unroll") for (int _i = 0; _i < 2; ++_i) { \
;         const unsigned _m0 = ldsb + (unsigned)((bufoff) + _i * 8192); const char* _gb = (const char*)(gbase); \
;         asm volatile("s_mov_b32 m0, %0\n\ts_nop 0\n\tglobal_load_lds_dwordx4 %1, %2" :: "s"(_m0), "v"((voff)[_i]), "s"(_gb) : "m0", "memory"); } } while (0)
; #define PG8_LDA(dst, b, h) do { _Pragma("unroll") for (int m = 0; m < 4; ++m) _Pragma("unroll") for (int k = 0; k < 2; ++k) dst[m][k] = *(const LAS bf16x8*)(lds + PG8_SA(b, h) + aoff + m * 2048 + k * 1024); } while (0)
; #define PG8_LDB(dst, b, h) do { _Pragma("unroll") for (int n = 0; n < 2; ++n) _Pragma("unroll") for (int k = 0; k < 2; ++k) dst[n][k] = *(const LAS bf16x8*)(lds + PG8_SB(b, h) + boff + n * 2048 + k * 1024); } while (0)
; #define PG8_MMA(ai, bj, At, Bt) do { __builtin_amdgcn_s_setprio(1); _Pragma("unroll") for (int m = 0; m < 4; ++m) _Pragma("unroll") for (int n = 0; n < 2; ++n) _Pragma("unroll") for (int k = 0; k < 2; ++k) \
;         acc[ai][bj][m][n] = __builtin_amdgcn_mfma_f32_16x16x32_bf16(Bt[n][k], At[m][k], acc[ai][bj][m][n], 0, 0, 0); __builtin_amdgcn_s_setprio(0); } while (0)
; #define PG8_WAIT_V(n) asm volatile("s_waitcnt vmcnt(" #n ")" ::: "memory")
; #define PG8_WAIT_L(n) asm volatile("s_waitcnt lgkmcnt(" #n ")" ::: "memory")
; template <class Epi, bool ALIGN_EPI>
; __device__ __forceinline__ void gemm_phase(LAS unsigned char* lds, const Gemm g, const StaticOrder& S, const Epi& E) {
;     ...
;         for (int t = 0; t < nt; t += 2) {
;             const bool last = (t == nt - 2);
;             const char* a1 = cA + (size_t)(t + 1) * kstep;
;             const char* a2 = last ? nA : cA + (size_t)(t + 2) * kstep; const char* b2 = last ? nB : cB + (size_t)(t + 2) * kstep;
;             const char* a3 = a2 + kstep; const char* b3 = b2 + kstep;
;             PG8_LDB(B0, 0, 0); PG8_LDB(B1, 0, 1); PG8_SCHED; PG8_LDA(At, 0, 0); PG8_STAGE(PG8_SA(1, 1), a1 + hstepA, voffA);
;             PG8_WAIT_V(8); PG8_WAIT_L(0); PG8_BAR; PG8_MMA(0, 0, At, B0); PG8_MMA(0, 1, At, B1); PG8_BAR; PG8_SCHED;
;             PG8_LDA(At, 0, 1); PG8_STAGE(PG8_SB(0, 0), b2, voffB); PG8_STAGE(PG8_SB(0, 1), b2 + hstepB, voffB); PG8_STAGE(PG8_SA(0, 0), a2, voffA);
;             PG8_WAIT_V(8); PG8_WAIT_L(0); PG8_BAR; PG8_MMA(1, 0, At, B0); PG8_MMA(1, 1, At, B1); PG8_BAR; PG8_SCHED;
.LBB0_150:
	s_add_u32 s4, s48, 0x100
	s_addc_u32 s5, s49, 0
	s_add_u32 s37, s54, 0x100
	s_addc_u32 s44, s55, 0
	s_mov_b32 s45, 0
	s_waitcnt lgkmcnt(0)
	s_add_i32 s51, s45, 2
	s_cmp_eq_u32 s67, s45
	s_cselect_b32 s56, s0, s37
	s_cselect_b32 s57, s1, s44
	s_cselect_b32 s54, s94, s4
	s_cselect_b32 s55, s95, s5
	s_add_u32 s48, s56, 0x80
	s_addc_u32 s49, s57, 0
	s_add_u32 s45, s37, s15
	s_addc_u32 s59, s44, 0
	s_add_u32 s58, s45, 0xffffff80
	s_addc_u32 s59, s59, -1
	s_mov_b32 m0, s68
	s_nop 0
	global_load_lds_dwordx4 v0, s[58:59]
	s_nop 0
	s_mov_b32 m0, s85
	s_nop 0
	global_load_lds_dwordx4 v240, s[58:59]
	s_waitcnt vmcnt(8)
	s_waitcnt lgkmcnt(0)
	s_nop 0
	s_barrier
	s_setprio 1
	s_waitcnt lgkmcnt(0)
	v_mfma_f32_16x16x32_bf16 v[172:175], v[108:111], v[156:159], 0
	v_mfma_f32_16x16x32_bf16 v[172:175], v[120:123], v[160:163], v[172:175]
	v_mfma_f32_16x16x32_bf16 v[168:171], v[128:131], v[156:159], 0
	v_mfma_f32_16x16x32_bf16 v[168:171], v[132:135], v[160:163], v[168:171]
	v_mfma_f32_16x16x32_bf16 v[140:143], v[136:139], v[156:159], 0
	v_mfma_f32_16x16x32_bf16 v[140:143], v[144:147], v[160:163], v[140:143]
	v_mfma_f32_16x16x32_bf16 v[124:127], v[148:151], v[156:159], 0
	v_mfma_f32_16x16x32_bf16 v[124:127], v[152:155], v[160:163], v[124:127]
	v_mfma_f32_16x16x32_bf16 v[100:103], v[148:151], v[164:167], 0
	v_mfma_f32_16x16x32_bf16 v[100:103], v[152:155], v[176:179], v[100:103]
	v_mfma_f32_16x16x32_bf16 v[104:107], v[136:139], v[164:167], 0
	v_mfma_f32_16x16x32_bf16 v[104:107], v[144:147], v[176:179], v[104:107]
	v_mfma_f32_16x16x32_bf16 v[112:115], v[128:131], v[164:167], 0
	v_mfma_f32_16x16x32_bf16 v[112:115], v[132:135], v[176:179], v[112:115]
	v_mfma_f32_16x16x32_bf16 v[116:119], v[108:111], v[164:167], 0
	v_mfma_f32_16x16x32_bf16 v[116:119], v[120:123], v[176:179], v[116:119]
	v_mfma_f32_16x16x32_bf16 v[96:99], v[108:111], v[180:183], 0
	v_mfma_f32_16x16x32_bf16 v[96:99], v[120:123], v[184:187], v[96:99]
	v_mfma_f32_16x16x32_bf16 v[92:95], v[128:131], v[180:183], 0
	v_mfma_f32_16x16x32_bf16 v[92:95], v[132:135], v[184:187], v[92:95]
	v_mfma_f32_16x16x32_bf16 v[88:91], v[136:139], v[180:183], 0
	v_mfma_f32_16x16x32_bf16 v[88:91], v[144:147], v[184:187], v[88:91]
	v_mfma_f32_16x16x32_bf16 v[84:87], v[148:151], v[180:183], 0
	v_mfma_f32_16x16x32_bf16 v[84:87], v[152:155], v[184:187], v[84:87]
	v_mfma_f32_16x16x32_bf16 v[68:71], v[148:151], v[188:191], 0
	v_mfma_f32_16x16x32_bf16 v[68:71], v[152:155], v[202:205], v[68:71]
	v_mfma_f32_16x16x32_bf16 v[72:75], v[136:139], v[188:191], 0
	v_mfma_f32_16x16x32_bf16 v[72:75], v[144:147], v[202:205], v[72:75]
	v_mfma_f32_16x16x32_bf16 v[76:79], v[128:131], v[188:191], 0
	v_mfma_f32_16x16x32_bf16 v[76:79], v[132:135], v[202:205], v[76:79]
	v_mfma_f32_16x16x32_bf16 v[80:83], v[108:111], v[188:191], 0
	v_mfma_f32_16x16x32_bf16 v[80:83], v[120:123], v[202:205], v[80:83]
	s_setprio 0
	s_barrier
	ds_read_b128 v[156:159], v245 offset:16384
	ds_read_b128 v[160:163], v245 offset:17408
	ds_read_b128 v[164:167], v245 offset:18432
	ds_read_b128 v[176:179], v245 offset:19456
	ds_read_b128 v[180:183], v245 offset:20480
	ds_read_b128 v[184:187], v245 offset:21504
	ds_read_b128 v[188:191], v245 offset:22528
	ds_read_b128 v[202:205], v245 offset:23552
	s_mov_b32 m0, s27
	s_nop 0
	global_load_lds_dwordx4 v195, s[54:55]
	s_add_u32 s58, s54, s15
	s_mov_b32 m0, s28
	s_nop 0
	global_load_lds_dwordx4 v241, s[54:55]
	s_addc_u32 s59, s55, 0
	s_mov_b32 m0, s29
	s_nop 0
	global_load_lds_dwordx4 v195, s[58:59]
	s_nop 0
	s_mov_b32 m0, s30
	s_nop 0
	global_load_lds_dwordx4 v241, s[58:59]
	s_nop 0
	s_mov_b32 m0, s26
	s_nop 0
	global_load_lds_dwordx4 v0, s[56:57]
	s_nop 0
	s_mov_b32 m0, s31
	s_nop 0
	global_load_lds_dwordx4 v240, s[56:57]
	s_waitcnt vmcnt(8)
	s_waitcnt lgkmcnt(0)
	s_barrier
	s_setprio 1
	s_waitcnt lgkmcnt(0)
	v_mfma_f32_16x16x32_bf16 v[64:67], v[108:111], v[156:159], 0
	v_mfma_f32_16x16x32_bf16 v[64:67], v[120:123], v[160:163], v[64:67]
	v_mfma_f32_16x16x32_bf16 v[60:63], v[128:131], v[156:159], 0
	v_mfma_f32_16x16x32_bf16 v[60:63], v[132:135], v[160:163], v[60:63]
	v_mfma_f32_16x16x32_bf16 v[56:59], v[136:139], v[156:159], 0
	v_mfma_f32_16x16x32_bf16 v[56:59], v[144:147], v[160:163], v[56:59]
	v_mfma_f32_16x16x32_bf16 v[52:55], v[148:151], v[156:159], 0
	v_mfma_f32_16x16x32_bf16 v[52:55], v[152:155], v[160:163], v[52:55]
	v_mfma_f32_16x16x32_bf16 v[36:39], v[148:151], v[164:167], 0
	v_mfma_f32_16x16x32_bf16 v[36:39], v[152:155], v[176:179], v[36:39]
	v_mfma_f32_16x16x32_bf16 v[40:43], v[136:139], v[164:167], 0
	v_mfma_f32_16x16x32_bf16 v[40:43], v[144:147], v[176:179], v[40:43]
	v_mfma_f32_16x16x32_bf16 v[44:47], v[128:131], v[164:167], 0
	v_mfma_f32_16x16x32_bf16 v[44:47], v[132:135], v[176:179], v[44:47]
	v_mfma_f32_16x16x32_bf16 v[48:51], v[108:111], v[164:167], 0
	v_mfma_f32_16x16x32_bf16 v[48:51], v[120:123], v[176:179], v[48:51]
	v_mfma_f32_16x16x32_bf16 v[32:35], v[108:111], v[180:183], 0
	v_mfma_f32_16x16x32_bf16 v[32:35], v[120:123], v[184:187], v[32:35]
	v_mfma_f32_16x16x32_bf16 v[28:31], v[128:131], v[180:183], 0
	v_mfma_f32_16x16x32_bf16 v[28:31], v[132:135], v[184:187], v[28:31]
	v_mfma_f32_16x16x32_bf16 v[24:27], v[136:139], v[180:183], 0
	v_mfma_f32_16x16x32_bf16 v[24:27], v[144:147], v[184:187], v[24:27]
	v_mfma_f32_16x16x32_bf16 v[20:23], v[148:151], v[180:183], 0
	v_mfma_f32_16x16x32_bf16 v[20:23], v[152:155], v[184:187], v[20:23]
	v_mfma_f32_16x16x32_bf16 v[4:7], v[148:151], v[188:191], 0
	v_mfma_f32_16x16x32_bf16 v[4:7], v[152:155], v[202:205], v[4:7]
	v_mfma_f32_16x16x32_bf16 v[8:11], v[136:139], v[188:191], 0
	v_mfma_f32_16x16x32_bf16 v[8:11], v[144:147], v[202:205], v[8:11]
	v_mfma_f32_16x16x32_bf16 v[12:15], v[128:131], v[188:191], 0
	v_mfma_f32_16x16x32_bf16 v[12:15], v[132:135], v[202:205], v[12:15]
	v_mfma_f32_16x16x32_bf16 v[16:19], v[108:111], v[188:191], 0
	v_mfma_f32_16x16x32_bf16 v[16:19], v[120:123], v[202:205], v[16:19]
	s_setprio 0
	s_barrier
; #define PG8_STAGE(bufoff, gbase, voff) do { _Pragma("unroll") for (int _i = 0; _i < 2; ++_i) { \
;         const unsigned _m0 = ldsb + (unsigned)((bufoff) + _i * 8192); const char* _gb = (const char*)(gbase); \
;         asm volatile("s_mov_b32 m0, %0\n\ts_nop 0\n\tglobal_load_lds_dwordx4 %1, %2" :: "s"(_m0), "v"((voff)[_i]), "s"(_gb) : "m0", "memory"); } } while (0)
; #define PG8_LDA(dst, b, h) do { _Pragma("unroll") for (int m = 0; m < 4; ++m) _Pragma("unroll") for (int k = 0; k < 2; ++k) dst[m][k] = *(const LAS bf16x8*)(lds + PG8_SA(b, h) + aoff + m * 2048 + k * 1024); } while (0)
; #define PG8_LDB(dst, b, h) do { _Pragma("unroll") for (int n = 0; n < 2; ++n) _Pragma("unroll") for (int k = 0; k < 2; ++k) dst[n][k] = *(const LAS bf16x8*)(lds + PG8_SB(b, h) + boff + n * 2048 + k * 1024); } while (0)
; #define PG8_MMA(ai, bj, At, Bt) do { __builtin_amdgcn_s_setprio(1); _Pragma("unroll") for (int m = 0; m < 4; ++m) _Pragma("unroll") for (int n = 0; n < 2; ++n) _Pragma("unroll") for (int k = 0; k < 2; ++k) \
;         acc[ai][bj][m][n] = __builtin_amdgcn_mfma_f32_16x16x32_bf16(Bt[n][k], At[m][k], acc[ai][bj][m][n], 0, 0, 0); __builtin_amdgcn_s_setprio(0); } while (0)
; #define PG8_WAIT_V(n) asm volatile("s_waitcnt vmcnt(" #n ")" ::: "memory")
; #define PG8_WAIT_L(n) asm volatile("s_waitcnt lgkmcnt(" #n ")" ::: "memory")
; #define PG8_BAR __builtin_amdgcn_s_barrier()
; #define PG8_SCHED __builtin_amdgcn_sched_barrier(0)
; template <class Epi, bool ALIGN_EPI>
; __device__ __forceinline__ void gemm_phase(LAS unsigned char* lds, const Gemm g, const StaticOrder& S, const Epi& E) {
;     ...
;             PG8_LDB(B0, 1, 0); PG8_LDB(B1, 1, 1); PG8_SCHED; PG8_LDA(At, 1, 0); PG8_STAGE(PG8_SA(0, 1), a2 + hstepA, voffA);
;             PG8_WAIT_V(8); PG8_WAIT_L(0); PG8_BAR; PG8_MMA(0, 0, At, B0); PG8_MMA(0, 1, At, B1); PG8_BAR; PG8_SCHED;
;             PG8_LDA(At, 1, 1); PG8_STAGE(PG8_SB(1, 0), b3, voffB); PG8_STAGE(PG8_SB(1, 1), b3 + hstepB, voffB); PG8_STAGE(PG8_SA(1, 0), a3, voffA);
;             PG8_WAIT_V(8); PG8_WAIT_L(0); PG8_BAR; PG8_MMA(1, 0, At, B0); PG8_MMA(1, 1, At, B1); PG8_BAR; PG8_SCHED;
;         }
	v_add_u32_e32 v132, 0x18000, v244
	v_add_u32_e32 v152, 0x1c000, v244
	ds_read_b128 v[108:111], v132
	ds_read_b128 v[120:123], v132 offset:1024
	ds_read_b128 v[128:131], v132 offset:2048
	ds_read_b128 v[132:135], v132 offset:3072
	ds_read_b128 v[136:139], v152
	ds_read_b128 v[144:147], v152 offset:1024
	ds_read_b128 v[148:151], v152 offset:2048
	ds_read_b128 v[152:155], v152 offset:3072
	ds_read_b128 v[156:159], v245 offset:32768
	ds_read_b128 v[160:163], v245 offset:33792
	ds_read_b128 v[164:167], v245 offset:34816
	ds_read_b128 v[176:179], v245 offset:35840
	ds_read_b128 v[180:183], v245 offset:36864
	ds_read_b128 v[184:187], v245 offset:37888
	ds_read_b128 v[188:191], v245 offset:38912
	ds_read_b128 v[202:205], v245 offset:39936
	s_add_u32 s56, s56, s15
	s_addc_u32 s57, s57, 0
	s_mov_b32 m0, s41
	s_nop 0
	global_load_lds_dwordx4 v0, s[56:57]
	s_nop 0
	s_mov_b32 m0, s42
	s_nop 0
	global_load_lds_dwordx4 v240, s[56:57]
	s_waitcnt vmcnt(8)
	s_waitcnt lgkmcnt(0)
	s_barrier
	s_setprio 1
	s_waitcnt lgkmcnt(0)
	v_mfma_f32_16x16x32_bf16 v[172:175], v[108:111], v[156:159], v[172:175]
	v_mfma_f32_16x16x32_bf16 v[172:175], v[120:123], v[160:163], v[172:175]
	v_mfma_f32_16x16x32_bf16 v[168:171], v[128:131], v[156:159], v[168:171]
	v_mfma_f32_16x16x32_bf16 v[168:171], v[132:135], v[160:163], v[168:171]
	v_mfma_f32_16x16x32_bf16 v[140:143], v[136:139], v[156:159], v[140:143]
	v_mfma_f32_16x16x32_bf16 v[140:143], v[144:147], v[160:163], v[140:143]
	v_mfma_f32_16x16x32_bf16 v[124:127], v[148:151], v[156:159], v[124:127]
	v_mfma_f32_16x16x32_bf16 v[124:127], v[152:155], v[160:163], v[124:127]
	v_mfma_f32_16x16x32_bf16 v[100:103], v[148:151], v[164:167], v[100:103]
	v_mfma_f32_16x16x32_bf16 v[100:103], v[152:155], v[176:179], v[100:103]
	v_mfma_f32_16x16x32_bf16 v[104:107], v[136:139], v[164:167], v[104:107]
	v_mfma_f32_16x16x32_bf16 v[104:107], v[144:147], v[176:179], v[104:107]
	v_mfma_f32_16x16x32_bf16 v[112:115], v[128:131], v[164:167], v[112:115]
	v_mfma_f32_16x16x32_bf16 v[112:115], v[132:135], v[176:179], v[112:115]
	v_mfma_f32_16x16x32_bf16 v[116:119], v[108:111], v[164:167], v[116:119]
	v_mfma_f32_16x16x32_bf16 v[116:119], v[120:123], v[176:179], v[116:119]
	v_mfma_f32_16x16x32_bf16 v[96:99], v[108:111], v[180:183], v[96:99]
	v_mfma_f32_16x16x32_bf16 v[96:99], v[120:123], v[184:187], v[96:99]
	v_mfma_f32_16x16x32_bf16 v[92:95], v[128:131], v[180:183], v[92:95]
	v_mfma_f32_16x16x32_bf16 v[92:95], v[132:135], v[184:187], v[92:95]
	v_mfma_f32_16x16x32_bf16 v[88:91], v[136:139], v[180:183], v[88:91]
	v_mfma_f32_16x16x32_bf16 v[88:91], v[144:147], v[184:187], v[88:91]
	v_mfma_f32_16x16x32_bf16 v[84:87], v[148:151], v[180:183], v[84:87]
	v_mfma_f32_16x16x32_bf16 v[84:87], v[152:155], v[184:187], v[84:87]
	v_mfma_f32_16x16x32_bf16 v[68:71], v[148:151], v[188:191], v[68:71]
	v_mfma_f32_16x16x32_bf16 v[68:71], v[152:155], v[202:205], v[68:71]
	v_mfma_f32_16x16x32_bf16 v[72:75], v[136:139], v[188:191], v[72:75]
	v_mfma_f32_16x16x32_bf16 v[72:75], v[144:147], v[202:205], v[72:75]
	v_mfma_f32_16x16x32_bf16 v[76:79], v[128:131], v[188:191], v[76:79]
	v_mfma_f32_16x16x32_bf16 v[76:79], v[132:135], v[202:205], v[76:79]
	v_mfma_f32_16x16x32_bf16 v[80:83], v[108:111], v[188:191], v[80:83]
	v_mfma_f32_16x16x32_bf16 v[80:83], v[120:123], v[202:205], v[80:83]
	s_setprio 0
	s_barrier
	ds_read_b128 v[156:159], v245 offset:49152
	ds_read_b128 v[160:163], v245 offset:50176
	ds_read_b128 v[164:167], v245 offset:51200
	ds_read_b128 v[176:179], v245 offset:52224
	ds_read_b128 v[180:183], v245 offset:53248
	ds_read_b128 v[184:187], v245 offset:54272
	ds_read_b128 v[188:191], v245 offset:55296
	ds_read_b128 v[202:205], v245 offset:56320
	s_add_u32 s54, s54, 0x80
	s_addc_u32 s55, s55, 0
	s_mov_b32 m0, s46
	s_nop 0
	global_load_lds_dwordx4 v195, s[54:55]
	s_nop 0
	s_mov_b32 m0, s50
	s_nop 0
	global_load_lds_dwordx4 v241, s[54:55]
	s_add_u32 s54, s58, 0x80
	s_addc_u32 s55, s59, 0
	s_mov_b32 m0, s61
	s_nop 0
	global_load_lds_dwordx4 v195, s[54:55]
	s_nop 0
	s_mov_b32 m0, s65
	s_nop 0
	global_load_lds_dwordx4 v241, s[54:55]
	s_nop 0
	s_mov_b32 m0, s53
	s_nop 0
	global_load_lds_dwordx4 v0, s[48:49]
	s_nop 0
	s_mov_b32 m0, s60
	s_nop 0
	global_load_lds_dwordx4 v240, s[48:49]
	s_waitcnt vmcnt(8)
	s_waitcnt lgkmcnt(0)
	s_nop 0
	s_barrier
	s_setprio 1
	s_waitcnt lgkmcnt(0)
	v_mfma_f32_16x16x32_bf16 v[64:67], v[108:111], v[156:159], v[64:67]
	v_mfma_f32_16x16x32_bf16 v[64:67], v[120:123], v[160:163], v[64:67]
	v_mfma_f32_16x16x32_bf16 v[60:63], v[128:131], v[156:159], v[60:63]
	v_mfma_f32_16x16x32_bf16 v[60:63], v[132:135], v[160:163], v[60:63]
	v_mfma_f32_16x16x32_bf16 v[56:59], v[136:139], v[156:159], v[56:59]
	v_mfma_f32_16x16x32_bf16 v[56:59], v[144:147], v[160:163], v[56:59]
	v_mfma_f32_16x16x32_bf16 v[52:55], v[148:151], v[156:159], v[52:55]
	v_mfma_f32_16x16x32_bf16 v[52:55], v[152:155], v[160:163], v[52:55]
	v_mfma_f32_16x16x32_bf16 v[36:39], v[148:151], v[164:167], v[36:39]
	v_mfma_f32_16x16x32_bf16 v[36:39], v[152:155], v[176:179], v[36:39]
	v_mfma_f32_16x16x32_bf16 v[40:43], v[136:139], v[164:167], v[40:43]
	v_mfma_f32_16x16x32_bf16 v[40:43], v[144:147], v[176:179], v[40:43]
	v_mfma_f32_16x16x32_bf16 v[44:47], v[128:131], v[164:167], v[44:47]
	v_mfma_f32_16x16x32_bf16 v[44:47], v[132:135], v[176:179], v[44:47]
	v_mfma_f32_16x16x32_bf16 v[48:51], v[108:111], v[164:167], v[48:51]
	v_mfma_f32_16x16x32_bf16 v[48:51], v[120:123], v[176:179], v[48:51]
	v_mfma_f32_16x16x32_bf16 v[32:35], v[108:111], v[180:183], v[32:35]
	v_mfma_f32_16x16x32_bf16 v[32:35], v[120:123], v[184:187], v[32:35]
	v_mfma_f32_16x16x32_bf16 v[28:31], v[128:131], v[180:183], v[28:31]
	v_mfma_f32_16x16x32_bf16 v[28:31], v[132:135], v[184:187], v[28:31]
	v_mfma_f32_16x16x32_bf16 v[24:27], v[136:139], v[180:183], v[24:27]
	v_mfma_f32_16x16x32_bf16 v[24:27], v[144:147], v[184:187], v[24:27]
	v_mfma_f32_16x16x32_bf16 v[20:23], v[148:151], v[180:183], v[20:23]
	v_mfma_f32_16x16x32_bf16 v[20:23], v[152:155], v[184:187], v[20:23]
	v_mfma_f32_16x16x32_bf16 v[4:7], v[148:151], v[188:191], v[4:7]
	v_mfma_f32_16x16x32_bf16 v[4:7], v[152:155], v[202:205], v[4:7]
	v_mfma_f32_16x16x32_bf16 v[8:11], v[136:139], v[188:191], v[8:11]
	v_mfma_f32_16x16x32_bf16 v[8:11], v[144:147], v[202:205], v[8:11]
	v_mfma_f32_16x16x32_bf16 v[12:15], v[128:131], v[188:191], v[12:15]
	v_mfma_f32_16x16x32_bf16 v[12:15], v[132:135], v[202:205], v[12:15]
	v_mfma_f32_16x16x32_bf16 v[16:19], v[108:111], v[188:191], v[16:19]
	v_mfma_f32_16x16x32_bf16 v[16:19], v[120:123], v[202:205], v[16:19]
	s_setprio 0
	s_barrier
	s_add_u32 s4, s4, 0x100
	s_addc_u32 s5, s5, 0
	s_add_u32 s37, s37, 0x100
	s_addc_u32 s44, s44, 0
	s_cmp_ge_u32 s51, s43
	s_mov_b32 s45, s51
